# SSD out pass 1: a_log + conv weights loaded first, counted waits so state fragments stream under vec/conv compute (on top of v18)
# speedup vs baseline: 1.0035x; 1.0035x over previous
;     __device__ __forceinline__ int lane_() const { return hw_lane(); }
; __device__ __forceinline__ float shfl_from(float x, int src_lane) { return __builtin_bit_cast(float, __builtin_amdgcn_ds_bpermute(src_lane << 2, __builtin_bit_cast(int, x))); }
; __device__ __forceinline__ void vec_load(Frame& F, const Ptrs& P, int b, int c, int h0, float& v0, float& v1) {
;     const float* DT = (const float*)(P.ws + WS_DT);
;     const int lane = F.lane_(), hl = F.wave >> 1, dir = F.wave & 1, h = h0 + hl;
;     const size_t row0 = (size_t)b * SEQ + c * 128;
;     v0 = DT[(row0 + lane) * 32 + dir * 16 + h]; v1 = DT[(row0 + 64 + lane) * 32 + dir * 16 + h];
; }
; __device__ __forceinline__ void vec_compute(Frame& F, const Ptrs& P, int b, int c, int h0, float v0, float v1, float* DEC) {
;     const int lane = F.lane_(), hl = F.wave >> 1, dir = F.wave & 1, h = h0 + hl;
;     const float A2 = -expf(dir ? P.alb[h] : P.alf[h]) * LOG2E;
;     float a0, a1, aend;
;     if (dir == 0) { const float p0 = incl_prefix(v0, lane), t0 = shfl_from(p0, 63), p1 = incl_prefix(v1, lane) + t0; a0 = A2 * p0; a1 = A2 * p1; aend = shfl_from(a1, 63); }
; template <class Wait>
; __device__ __forceinline__ void out_unit(Frame& F, const Ptrs& P, int b, int c, int g, const Wait& wait) {
;     ...
;     } else {
;     float dv0, dv1; vec_load(F, P, b, c, h0, dv0, dv1);
;     ConvRaw R2;
;     conv_load(R2, XBC, b, c, col2, rg2);
;     { const unsigned char* blk = SB + ((((size_t)b * 64 + c) * 2 + 0) * 16 + h) * 16384 + hi * 512 + r32 * 16;
; #pragma unroll
;       for (int pb = 0; pb < 2; ++pb)
; #pragma unroll
;           for (int ks = 0; ks < 8; ++ks) A0[pb][ks] = *(const bf16x8*)(blk + (pb * 8 + ks) * 1024); }
;     vec_compute(F, P, b, c, h0, dv0, dv1, nullptr);
.LBB0_713:
	v_mbcnt_lo_u32_b32 v0, -1, 0
	v_mbcnt_hi_u32_b32 v0, -1, v0
	s_xor_b64 s[52:53], s[0:1], -1
	v_add_u32_e32 v224, s60, v0
	s_or_b32 s0, s2, s12
	v_ashrrev_i32_e32 v142, 7, v224
	v_and_b32_e32 v140, 7, v224
	v_bfe_u32 v141, v224, 3, 4
	v_add_u32_e32 v0, s0, v142
	s_waitcnt lgkmcnt(0)
	v_lshlrev_b32_e32 v1, 3, v140
	v_and_b32_e32 v222, 31, v224
	v_bfe_u32 v223, v224, 5, 1
	v_lshl_or_b32 v130, v0, 6, v1
	v_lshlrev_b32_e32 v0, 3, v141
	s_add_i32 s18, s0, s63
	s_and_b64 vcc, exec, s[52:53]
	v_ashrrev_i32_e32 v131, 31, v130
	v_lshlrev_b32_e32 v200, 9, v223
	v_lshlrev_b32_e32 v128, 4, v222
	v_add_u32_e32 v143, s64, v0
	v_or_b32_e32 v144, s13, v0
	s_mov_b64 s[0:1], -1
	s_cbranch_vccz .LBB0_719
	v_mbcnt_lo_u32_b32 v0, -1, 0
	v_mbcnt_hi_u32_b32 v0, -1, v0
	s_lshl_b64 s[0:1], s[18:19], 2
	v_ashrrev_i32_e32 v1, 31, v0
	v_lshl_add_u64 v[2:3], s[44:45], 0, v[0:1]
	v_lshlrev_b64 v[2:3], 7, v[2:3]
	v_lshl_add_u64 v[0:1], s[46:47], 0, v[0:1]
	v_lshl_add_u64 v[2:3], s[22:23], 0, v[2:3]
	v_lshlrev_b64 v[0:1], 7, v[0:1]
	v_lshl_add_u64 v[2:3], v[2:3], 0, s[0:1]
	v_lshl_add_u64 v[0:1], s[22:23], 0, v[0:1]
	v_lshl_add_u64 v[0:1], v[0:1], 0, s[0:1]
	global_load_dword v25, v[2:3], off
	global_load_dword v28, v[0:1], off
	s_add_u32 s98, s85, s0
	s_addc_u32 s99, s84, s1
	global_load_dword v24, v201, s[98:99]
	v_lshlrev_b64 v[190:191], 2, v[130:131]
	v_lshl_add_u64 v[192:193], s[24:25], 0, v[190:191]
	global_load_dwordx4 v[158:161], v[192:193], off offset:16
	global_load_dwordx4 v[162:165], v[192:193], off
	v_lshl_add_u64 v[192:193], s[30:31], 0, v[190:191]
	global_load_dwordx4 v[166:169], v[192:193], off offset:16
	global_load_dwordx4 v[170:173], v[192:193], off
	v_lshl_add_u64 v[192:193], s[36:37], 0, v[190:191]
	global_load_dwordx4 v[174:177], v[192:193], off offset:16
	global_load_dwordx4 v[178:181], v[192:193], off
	v_lshl_add_u64 v[192:193], s[26:27], 0, v[190:191]
	global_load_dwordx4 v[182:185], v[192:193], off offset:16
	global_load_dwordx4 v[186:189], v[192:193], off
	v_max_i32_e32 v2, 0, v143
	v_mov_b32_e32 v3, v201
	v_lshl_add_u64 v[0:1], v[130:131], 1, s[14:15]
	v_lshl_add_u64 v[2:3], s[42:43], 0, v[2:3]
	v_mad_u64_u32 v[4:5], s[2:3], v2, s87, v[0:1]
	v_or_b32_e32 v2, s42, v144
	v_mad_i32_i24 v5, v3, s87, v5
	v_mad_u64_u32 v[2:3], s[2:3], v2, s87, v[0:1]
	v_mad_i32_i24 v3, s43, v203, v3
	global_load_dwordx4 v[12:15], v[4:5], off
	global_load_dwordx4 v[120:123], v[2:3], off
	v_add_u32_e32 v2, 2, v143
	v_mov_b32_e32 v3, v201
	v_lshl_add_u64 v[2:3], s[42:43], 0, v[2:3]
	v_mad_u64_u32 v[4:5], s[2:3], v2, s87, v[0:1]
	v_mad_i32_i24 v5, v3, s87, v5
	v_add_u32_e32 v2, 3, v143
	v_mov_b32_e32 v3, v201
	v_lshl_add_u64 v[2:3], s[42:43], 0, v[2:3]
	v_mad_u64_u32 v[6:7], s[2:3], v2, s87, v[0:1]
	v_mad_i32_i24 v7, v3, s87, v7
	v_add_u32_e32 v2, 4, v143
	v_mov_b32_e32 v3, v201
	v_lshl_add_u64 v[2:3], s[42:43], 0, v[2:3]
	global_load_dwordx4 v[124:127], v[4:5], off
	global_load_dwordx4 v[60:63], v[6:7], off
	v_mad_u64_u32 v[4:5], s[2:3], v2, s87, v[0:1]
	v_mad_i32_i24 v5, v3, s87, v5
	v_add_u32_e32 v2, 5, v143
	v_mov_b32_e32 v3, v201
	v_lshl_add_u64 v[2:3], s[42:43], 0, v[2:3]
	v_mad_u64_u32 v[6:7], s[2:3], v2, s87, v[0:1]
	v_mad_i32_i24 v7, v3, s87, v7
	v_add_u32_e32 v2, 6, v143
	v_mov_b32_e32 v3, v201
	v_lshl_add_u64 v[2:3], s[42:43], 0, v[2:3]
	global_load_dwordx4 v[56:59], v[4:5], off
	global_load_dwordx4 v[52:55], v[6:7], off
	v_mad_u64_u32 v[4:5], s[2:3], v2, s87, v[0:1]
	v_mad_i32_i24 v5, v3, s87, v5
	v_add_u32_e32 v2, 7, v143
	v_mov_b32_e32 v3, v201
	v_lshl_add_u64 v[2:3], s[42:43], 0, v[2:3]
	v_mad_u64_u32 v[6:7], s[2:3], v2, s87, v[0:1]
	v_mad_i32_i24 v7, v3, s87, v7
	v_add_u32_e32 v2, 8, v143
	v_mov_b32_e32 v3, v201
	v_lshl_add_u64 v[2:3], s[42:43], 0, v[2:3]
	global_load_dwordx4 v[44:47], v[4:5], off
	global_load_dwordx4 v[8:11], v[6:7], off
	v_mad_u64_u32 v[4:5], s[2:3], v2, s87, v[0:1]
	v_add_u32_e32 v2, 9, v143
	v_min_u32_e32 v2, 0x1fff, v2
	v_or_b32_e32 v2, s42, v2
	v_mad_u64_u32 v[0:1], s[2:3], v2, s87, v[0:1]
	s_add_u32 s2, s50, s18
	s_addc_u32 s3, s51, 0
	s_lshl_b64 s[2:3], s[2:3], 14
	s_add_u32 s2, s58, s2
	v_mad_i32_i24 v5, v3, s87, v5
	v_mad_i32_i24 v1, s43, v203, v1
	s_addc_u32 s3, s59, s3
	global_load_dwordx4 v[4:7], v[4:5], off
	s_nop 0
	global_load_dwordx4 v[20:23], v[0:1], off
	v_lshl_add_u64 v[0:1], s[2:3], 0, v[200:201]
	v_mov_b32_e32 v129, v201
	v_lshl_add_u64 v[26:27], v[0:1], 0, v[128:129]
	v_add_co_u32_e32 v30, vcc, s88, v26
	s_add_u32 s0, s85, s0
	s_nop 0
	v_addc_co_u32_e32 v31, vcc, 0, v27, vcc
	v_add_co_u32_e32 v32, vcc, s89, v26
	s_nop 1
	v_addc_co_u32_e32 v33, vcc, 0, v27, vcc
	s_addc_u32 s1, s84, s1
	global_load_dwordx4 v[0:3], v[26:27], off
	global_load_dwordx4 v[108:111], v[26:27], off offset:1024
	global_load_dwordx4 v[96:99], v[26:27], off offset:2048
	global_load_dwordx4 v[84:87], v[26:27], off offset:3072
	global_load_dwordx4 v[88:91], v[30:31], off
	global_load_dwordx4 v[76:79], v[30:31], off offset:1024
	global_load_dwordx4 v[68:71], v[30:31], off offset:2048
	global_load_dwordx4 v[64:67], v[30:31], off offset:3072
	global_load_dwordx4 v[16:19], v[32:33], off
	global_load_dwordx4 v[116:119], v[32:33], off offset:1024
	global_load_dwordx4 v[112:115], v[32:33], off offset:2048
	global_load_dwordx4 v[104:107], v[32:33], off offset:3072
	v_add_co_u32_e32 v26, vcc, s90, v26
	s_nop 1
	v_addc_co_u32_e32 v27, vcc, 0, v27, vcc
	global_load_dwordx4 v[100:103], v[26:27], off
	global_load_dwordx4 v[92:95], v[26:27], off offset:1024
	global_load_dwordx4 v[80:83], v[26:27], off offset:2048
	global_load_dwordx4 v[72:75], v[26:27], off offset:3072
	v_mbcnt_lo_u32_b32 v29, -1, 0
	v_mbcnt_hi_u32_b32 v29, -1, v29
	v_cmp_gt_i32_e64 s[0:1], 32, v29
	s_waitcnt vmcnt(34)
	v_mul_f32_e32 v26, 0x3fb8aa3b, v24
	v_fma_f32 v27, v24, s91, -v26
	v_rndne_f32_e32 v30, v26
	v_fmac_f32_e32 v27, 0x32a5705f, v24
	v_sub_f32_e32 v26, v26, v30
	v_add_f32_e32 v26, v26, v27
	v_exp_f32_e32 v26, v26
	v_cvt_i32_f32_e32 v27, v30
	v_cmp_ngt_f32_e32 vcc, s92, v24
	v_ldexp_f32 v26, v26, v27
	s_nop 0
	v_cndmask_b32_e32 v26, 0, v26, vcc
	v_cmp_nlt_f32_e32 vcc, s93, v24
	s_nop 1
	v_cndmask_b32_e32 v24, v212, v26, vcc
	v_mul_f32_e32 v24, 0xbfb8aa3b, v24
	s_and_b64 vcc, exec, s[28:29]
	s_cbranch_vccz .LBB0_716
;     __device__ __forceinline__ int lane_() const { return hw_lane(); }
; __device__ __forceinline__ float shfl_from(float x, int src_lane) { return __builtin_bit_cast(float, __builtin_amdgcn_ds_bpermute(src_lane << 2, __builtin_bit_cast(int, x))); }
; __device__ __forceinline__ float incl_suffix(float x, int lane) {
; #pragma unroll
;     for (int o = 1; o < 64; o <<= 1) { const float t = shfl_from(x, lane + o < 64 ? lane + o : lane); if (lane + o < 64) x += t; }
;     return x;
; }
; __device__ __forceinline__ void vec_load(Frame& F, const Ptrs& P, int b, int c, int h0, float& v0, float& v1) {
;     const float* DT = (const float*)(P.ws + WS_DT);
;     const int lane = F.lane_(), hl = F.wave >> 1, dir = F.wave & 1, h = h0 + hl;
;     const size_t row0 = (size_t)b * SEQ + c * 128;
;     v0 = DT[(row0 + lane) * 32 + dir * 16 + h]; v1 = DT[(row0 + 64 + lane) * 32 + dir * 16 + h];
; }
; __device__ __forceinline__ void vec_compute(Frame& F, const Ptrs& P, int b, int c, int h0, float v0, float v1, float* DEC) {
;     const int lane = F.lane_(), hl = F.wave >> 1, dir = F.wave & 1, h = h0 + hl;
;     const float A2 = -expf(dir ? P.alb[h] : P.alf[h]) * LOG2E;
;     float a0, a1, aend;
;     if (dir == 0) { const float p0 = incl_prefix(v0, lane), t0 = shfl_from(p0, 63), p1 = incl_prefix(v1, lane) + t0; a0 = A2 * p0; a1 = A2 * p1; aend = shfl_from(a1, 63); }
;     else { const float s1 = incl_suffix(v1, lane), t1 = shfl_from(s1, 0), s0 = incl_suffix(v0, lane) + t1; a0 = A2 * s0; a1 = A2 * s1; aend = shfl_from(a0, 0); }
	v_cmp_gt_i32_e32 vcc, 63, v29
	v_lshlrev_b32_e32 v30, 2, v29
	v_add_u32_e32 v31, 8, v30
	v_addc_co_u32_e64 v26, s[2:3], 0, v29, vcc
	v_lshlrev_b32_e32 v26, 2, v26
	ds_bpermute_b32 v27, v26, v28
	ds_bpermute_b32 v26, v26, v25
	v_cmp_gt_i32_e64 s[2:3], 62, v29
	v_add_u32_e32 v33, 16, v30
	v_cmp_gt_i32_e64 s[4:5], 60, v29
	s_waitcnt lgkmcnt(1)
	v_add_f32_e32 v27, v28, v27
	v_cndmask_b32_e32 v27, v28, v27, vcc
	v_cndmask_b32_e64 v31, v30, v31, s[2:3]
	s_waitcnt lgkmcnt(0)
	v_add_f32_e32 v26, v25, v26
	ds_bpermute_b32 v32, v31, v27
	v_cndmask_b32_e32 v26, v25, v26, vcc
	ds_bpermute_b32 v31, v31, v26
	v_add_u32_e32 v34, 32, v30
	v_cmp_gt_i32_e64 s[6:7], 56, v29
	s_waitcnt lgkmcnt(1)
	v_add_f32_e32 v32, v27, v32
	v_cndmask_b32_e64 v27, v27, v32, s[2:3]
	v_cndmask_b32_e64 v32, v30, v33, s[4:5]
	s_waitcnt lgkmcnt(0)
	v_add_f32_e32 v31, v26, v31
	ds_bpermute_b32 v33, v32, v27
	v_cndmask_b32_e64 v26, v26, v31, s[2:3]
	ds_bpermute_b32 v31, v32, v26
	v_add_u32_e32 v32, 64, v30
	v_cmp_gt_i32_e32 vcc, 48, v29
	s_waitcnt lgkmcnt(1)
	v_add_f32_e32 v33, v27, v33
	v_cndmask_b32_e64 v27, v27, v33, s[4:5]
	v_cndmask_b32_e64 v33, v30, v34, s[6:7]
	s_waitcnt lgkmcnt(0)
	v_add_f32_e32 v31, v26, v31
	ds_bpermute_b32 v34, v33, v27
	v_cndmask_b32_e64 v26, v26, v31, s[4:5]
	ds_bpermute_b32 v31, v33, v26
	v_cndmask_b32_e32 v32, v30, v32, vcc
	s_waitcnt lgkmcnt(1)
	v_add_f32_e32 v34, v27, v34
	v_cndmask_b32_e64 v27, v27, v34, s[6:7]
	s_waitcnt lgkmcnt(0)
	v_add_f32_e32 v31, v26, v31
	ds_bpermute_b32 v34, v32, v27
	v_cndmask_b32_e64 v26, v26, v31, s[6:7]
	ds_bpermute_b32 v31, v32, v26
	v_add_u32_e32 v32, 0x80, v30
	v_cndmask_b32_e64 v30, v30, v32, s[0:1]
	s_waitcnt lgkmcnt(1)
	v_add_f32_e32 v33, v27, v34
	v_cndmask_b32_e32 v27, v27, v33, vcc
	s_waitcnt lgkmcnt(0)
	v_add_f32_e32 v31, v26, v31
	ds_bpermute_b32 v32, v30, v27
	v_cndmask_b32_e32 v31, v26, v31, vcc
	ds_bpermute_b32 v30, v30, v31
	s_waitcnt lgkmcnt(1)
	v_add_f32_e32 v26, v27, v32
	v_cndmask_b32_e64 v26, v27, v26, s[0:1]
	s_waitcnt lgkmcnt(0)
	v_add_f32_e32 v27, v31, v30
	v_readlane_b32 s2, v26, 0
	v_cndmask_b32_e64 v27, v31, v27, s[0:1]
	s_nop 0
	v_add_f32_e32 v27, s2, v27
	v_pk_mul_f32 v[26:27], v[24:25], v[26:27] op_sel_hi:[0,1]
	s_nop 0
	v_readlane_b32 s2, v27, 0
	s_cbranch_execz .LBB0_717
	s_branch .LBB0_718

; #define LAS __attribute__((address_space(3)))
; __device__ __forceinline__ float lo16(unsigned u) { return __uint_as_float(u << 16); }
; template <class Put>
; __device__ __forceinline__ void conv_compute(const ConvRaw& R, const float* cw, const float* cb, int col0, int rg, const Put& put) {
;     const f32x4 w0a = *(const f32x4*)(cw + col0), w0b = *(const f32x4*)(cw + col0 + 4), w1a = *(const f32x4*)(cw + XBCW + col0), w1b = *(const f32x4*)(cw + XBCW + col0 + 4);
;     const f32x4 w2a = *(const f32x4*)(cw + 2 * XBCW + col0), w2b = *(const f32x4*)(cw + 2 * XBCW + col0 + 4), ba = *(const f32x4*)(cb + col0), bb = *(const f32x4*)(cb + col0 + 4);
;     const int r0 = 8 * rg;
; #pragma unroll
;     for (int rr = 0; rr < 8; ++rr) {
;         const u32x4 xm = R.r[rr], x0 = R.r[rr + 1], xp = R.r[rr + 2]; u32x4 o;
; #pragma unroll
;         for (int e = 0; e < 4; ++e) {
;             const float wl0 = e < 2 ? w0a[2 * e] : w0b[2 * e - 4], wh0 = e < 2 ? w0a[2 * e + 1] : w0b[2 * e - 3];
;             const float wl1 = e < 2 ? w1a[2 * e] : w1b[2 * e - 4], wh1 = e < 2 ? w1a[2 * e + 1] : w1b[2 * e - 3];
;             const float wl2 = e < 2 ? w2a[2 * e] : w2b[2 * e - 4], wh2 = e < 2 ? w2a[2 * e + 1] : w2b[2 * e - 3];
;             const float bl = e < 2 ? ba[2 * e] : bb[2 * e - 4], bh = e < 2 ? ba[2 * e + 1] : bb[2 * e - 3];
;             const float vl = bl + wl0 * lo16(xm[e]) + wl1 * lo16(x0[e]) + wl2 * lo16(xp[e]);
;             const float vh = bh + wh0 * hi16(xm[e]) + wh1 * hi16(x0[e]) + wh2 * hi16(xp[e]);
;             o[e] = cvtpk(silu_fast(vl), silu_fast(vh));
;         }
;         put(r0 + rr, o);
;     }
; __device__ __forceinline__ void vec_compute(Frame& F, const Ptrs& P, int b, int c, int h0, float v0, float v1, float* DEC) {
;     ...
;     else { const float s1 = incl_suffix(v1, lane), t1 = shfl_from(s1, 0), s0 = incl_suffix(v0, lane) + t1; a0 = A2 * s0; a1 = A2 * s1; aend = shfl_from(a0, 0); }
;     LAS float* V = (LAS float*)(F.lds + L_VEC) + (hl * 2 + dir) * 512;
;     const float g0 = a0 - log2f(v0), g1 = a1 - log2f(v1);
;     V[lane] = a0; V[64 + lane] = a1; V[128 + lane] = g0; V[192 + lane] = g1; V[256 + lane] = v0; V[320 + lane] = v1;
;     V[384 + lane] = __builtin_amdgcn_exp2f(aend - g0); V[448 + lane] = __builtin_amdgcn_exp2f(aend - g1);
;     if (DEC && lane == 0) DEC[(((size_t)b * 64 + c) * 2 + dir) * 16 + h] = __builtin_amdgcn_exp2f(aend);
.LBB0_718:
	s_waitcnt vmcnt(16)
	v_or_b32_e32 v24, s97, v141
	v_cmp_eq_u32_e32 vcc, 15, v141
	s_and_b64 s[0:1], s[48:49], vcc
	v_cmp_ne_u32_e32 vcc, 0, v24
	v_cndmask_b32_e64 v147, v21, 0, s[0:1]
	v_cndmask_b32_e64 v148, v20, 0, s[0:1]
	v_cndmask_b32_e32 v150, 0, v15, vcc
	v_cndmask_b32_e32 v138, 0, v14, vcc
	v_cndmask_b32_e32 v139, 0, v13, vcc
	v_cndmask_b32_e32 v133, 0, v12, vcc
	v_cmp_gt_f32_e32 vcc, s94, v25
	v_cndmask_b32_e64 v145, v23, 0, s[0:1]
	v_cndmask_b32_e64 v146, v22, 0, s[0:1]
	v_cndmask_b32_e32 v12, 0, v218, vcc
	v_cndmask_b32_e64 v13, 0, 32, vcc
	v_cmp_gt_f32_e32 vcc, s94, v28
	v_ldexp_f32 v13, v25, v13
	v_log_f32_e32 v13, v13
	v_cndmask_b32_e64 v14, 0, 32, vcc
	v_ldexp_f32 v14, v28, v14
	v_log_f32_e32 v14, v14
	v_sub_f32_e32 v12, v13, v12
	v_cndmask_b32_e32 v13, 0, v218, vcc
	v_sub_f32_e32 v12, v27, v12
	v_sub_f32_e32 v13, v14, v13
	v_sub_f32_e32 v13, v26, v13
	v_lshl_add_u32 v14, v29, 2, s86
	ds_write2st64_b32 v14, v27, v26 offset1:1
	ds_write2st64_b32 v14, v12, v13 offset0:2 offset1:3
	ds_write2st64_b32 v14, v25, v28 offset0:4 offset1:5
	v_sub_f32_e32 v12, s2, v12
	v_sub_f32_e32 v13, s2, v13
	v_exp_f32_e32 v12, v12
	v_exp_f32_e32 v13, v13
	v_lshlrev_b64 v[28:29], 2, v[130:131]
	v_lshl_add_u64 v[20:21], s[24:25], 0, v[28:29]
	v_lshl_add_u64 v[30:31], s[36:37], 0, v[28:29]
	ds_write2st64_b32 v14, v12, v13 offset0:6 offset1:7
	v_mov_b32_e32 v12, v158
	v_mov_b32_e32 v13, v159
	v_mov_b32_e32 v14, v160
	v_mov_b32_e32 v15, v161
	v_mov_b32_e32 v32, v162
	v_mov_b32_e32 v33, v163
	v_mov_b32_e32 v34, v164
	v_mov_b32_e32 v35, v165
	v_lshl_add_u64 v[20:21], s[30:31], 0, v[28:29]
	v_lshl_add_u64 v[48:49], s[26:27], 0, v[28:29]
	v_mov_b32_e32 v24, v166
	v_mov_b32_e32 v25, v167
	v_mov_b32_e32 v26, v168
	v_mov_b32_e32 v27, v169
	v_mov_b32_e32 v36, v170
	v_mov_b32_e32 v37, v171
	v_mov_b32_e32 v38, v172
	v_mov_b32_e32 v39, v173
	s_nop 0
	v_mov_b32_e32 v20, v174
	v_mov_b32_e32 v21, v175
	v_mov_b32_e32 v22, v176
	v_mov_b32_e32 v23, v177
	v_mov_b32_e32 v40, v178
	v_mov_b32_e32 v41, v179
	v_mov_b32_e32 v42, v180
	v_mov_b32_e32 v43, v181
	s_nop 0
	v_mov_b32_e32 v28, v182
	v_mov_b32_e32 v29, v183
	v_mov_b32_e32 v30, v184
	v_mov_b32_e32 v31, v185
	s_nop 0
	v_mov_b32_e32 v48, v186
	v_mov_b32_e32 v49, v187
	v_mov_b32_e32 v50, v188
	v_mov_b32_e32 v51, v189
	v_lshlrev_b32_e32 v134, 1, v140
	v_lshrrev_b32_e32 v135, 1, v141
	v_and_or_b32 v134, v134, 8, v135
	v_lshlrev_b32_e32 v132, 14, v142
	v_lshlrev_b32_e32 v134, 10, v134
	v_add3_u32 v132, s69, v132, v134
	v_lshlrev_b32_e32 v134, 9, v141
	v_lshlrev_b32_e32 v135, 4, v140
	v_and_b32_e32 v134, 0x200, v134
	v_and_b32_e32 v135, 48, v135
	v_add3_u32 v149, v132, v134, v135
	v_lshlrev_b32_e32 v132, 16, v133
	v_and_b32_e32 v133, 0xffff0000, v133
	v_lshlrev_b32_e32 v134, 16, v120
	v_and_b32_e32 v135, 0xffff0000, v120
	v_or_b32_e32 v202, s68, v222
	v_lshlrev_b32_e32 v204, 3, v223
	s_mov_b64 s[0:1], 0
	s_waitcnt vmcnt(16)
	v_pk_fma_f32 v[132:133], v[32:33], v[132:133], v[48:49]
	s_nop 0
	v_pk_fma_f32 v[136:137], v[36:37], v[134:135], v[132:133]
	v_lshlrev_b32_e32 v132, 16, v124
	v_and_b32_e32 v133, 0xffff0000, v124
	v_pk_fma_f32 v[136:137], v[40:41], v[132:133], v[136:137]
	v_lshlrev_b32_e32 v124, 16, v125
	v_mul_f32_e32 v120, 0xbfb8aa3b, v136
	v_exp_f32_e32 v120, v120
	v_and_b32_e32 v125, 0xffff0000, v125
	v_add_f32_e32 v120, 1.0, v120
	v_rcp_f32_e32 v152, v120
	v_mul_f32_e32 v120, 0xbfb8aa3b, v137
	v_exp_f32_e32 v120, v120
	s_nop 0
	v_add_f32_e32 v120, 1.0, v120
	v_rcp_f32_e32 v153, v120
	s_nop 0
	v_pk_mul_f32 v[136:137], v[136:137], v[152:153]
	s_nop 0
	v_cvt_pk_bf16_f32 v120, v136, v137
	v_lshlrev_b32_e32 v136, 16, v139
	v_and_b32_e32 v137, 0xffff0000, v139
	v_pk_fma_f32 v[152:153], v[34:35], v[136:137], v[50:51]
	v_lshlrev_b32_e32 v136, 16, v121
	v_and_b32_e32 v137, 0xffff0000, v121
	v_pk_fma_f32 v[152:153], v[38:39], v[136:137], v[152:153]
	s_nop 0
	v_pk_fma_f32 v[152:153], v[42:43], v[124:125], v[152:153]
	s_nop 0
	v_mul_f32_e32 v121, 0xbfb8aa3b, v152
	v_exp_f32_e32 v121, v121
	s_nop 0
	v_add_f32_e32 v121, 1.0, v121
	v_rcp_f32_e32 v154, v121
	v_mul_f32_e32 v121, 0xbfb8aa3b, v153
	v_exp_f32_e32 v121, v121
	s_nop 0
	v_add_f32_e32 v121, 1.0, v121
	v_rcp_f32_e32 v155, v121
	s_nop 0
	v_pk_mul_f32 v[152:153], v[152:153], v[154:155]
	s_nop 0
	v_cvt_pk_bf16_f32 v121, v152, v153
	v_lshlrev_b32_e32 v152, 16, v138
	v_and_b32_e32 v153, 0xffff0000, v138
	v_pk_fma_f32 v[138:139], v[12:13], v[152:153], v[28:29]
	v_lshlrev_b32_e32 v152, 16, v122
	v_and_b32_e32 v153, 0xffff0000, v122
	v_pk_fma_f32 v[154:155], v[24:25], v[152:153], v[138:139]
	v_lshlrev_b32_e32 v138, 16, v126
	v_and_b32_e32 v139, 0xffff0000, v126
	v_pk_fma_f32 v[154:155], v[20:21], v[138:139], v[154:155]
	v_lshlrev_b32_e32 v126, 16, v127
	v_mul_f32_e32 v122, 0xbfb8aa3b, v154
	v_exp_f32_e32 v122, v122
	v_and_b32_e32 v127, 0xffff0000, v127
	v_add_f32_e32 v122, 1.0, v122
	v_rcp_f32_e32 v156, v122
	v_mul_f32_e32 v122, 0xbfb8aa3b, v155
	v_exp_f32_e32 v122, v122
	s_nop 0
	v_add_f32_e32 v122, 1.0, v122
	v_rcp_f32_e32 v157, v122
	s_nop 0
	v_pk_mul_f32 v[154:155], v[154:155], v[156:157]
	s_nop 0
	v_cvt_pk_bf16_f32 v122, v154, v155
	v_lshlrev_b32_e32 v154, 16, v150
	v_and_b32_e32 v155, 0xffff0000, v150
	v_pk_fma_f32 v[150:151], v[14:15], v[154:155], v[30:31]
	v_lshlrev_b32_e32 v154, 16, v123
	v_and_b32_e32 v155, 0xffff0000, v123
	v_pk_fma_f32 v[150:151], v[26:27], v[154:155], v[150:151]
	s_nop 0
	v_pk_fma_f32 v[150:151], v[22:23], v[126:127], v[150:151]
	s_nop 0
	v_mul_f32_e32 v123, 0xbfb8aa3b, v150
	v_exp_f32_e32 v123, v123
	s_nop 0
	v_add_f32_e32 v123, 1.0, v123
	v_rcp_f32_e32 v156, v123
	v_mul_f32_e32 v123, 0xbfb8aa3b, v151
	v_exp_f32_e32 v123, v123
	s_nop 0
; __device__ __forceinline__ unsigned cvtpk(float lo, float hi) { f32x2_t v = {lo, hi}; bf16x2_t b = __builtin_convertvector(v, bf16x2_t); return __builtin_bit_cast(unsigned, b); }
; __device__ __forceinline__ float lo16(unsigned u) { return __uint_as_float(u << 16); }
; __device__ __forceinline__ float hi16(unsigned u) { return __uint_as_float(u & 0xffff0000u); }
; __device__ __forceinline__ float silu_fast(float v) { return v * __builtin_amdgcn_rcpf(1.f + __builtin_amdgcn_exp2f(-v * LOG2E)); }
; __device__ __forceinline__ unsigned cvtpk(float lo, float hi) { f32x2_t v = {lo, hi}; bf16x2_t b = __builtin_convertvector(v, bf16x2_t); return __builtin_bit_cast(unsigned, b); }
; __device__ __forceinline__ float lo16(unsigned u) { return __uint_as_float(u << 16); }
; __device__ __forceinline__ float hi16(unsigned u) { return __uint_as_float(u & 0xffff0000u); }
; __device__ __forceinline__ float silu_fast(float v) { return v * __builtin_amdgcn_rcpf(1.f + __builtin_amdgcn_exp2f(-v * LOG2E)); }
; template <class Put>
; __device__ __forceinline__ void conv_compute(const ConvRaw& R, const float* cw, const float* cb, int col0, int rg, const Put& put) {
;     ...
;     for (int rr = 0; rr < 8; ++rr) {
;         const u32x4 xm = R.r[rr], x0 = R.r[rr + 1], xp = R.r[rr + 2]; u32x4 o;
; #pragma unroll
;         for (int e = 0; e < 4; ++e) {
;             const float wl0 = e < 2 ? w0a[2 * e] : w0b[2 * e - 4], wh0 = e < 2 ? w0a[2 * e + 1] : w0b[2 * e - 3];
;             const float wl1 = e < 2 ? w1a[2 * e] : w1b[2 * e - 4], wh1 = e < 2 ? w1a[2 * e + 1] : w1b[2 * e - 3];
;             const float wl2 = e < 2 ? w2a[2 * e] : w2b[2 * e - 4], wh2 = e < 2 ? w2a[2 * e + 1] : w2b[2 * e - 3];
;             const float bl = e < 2 ? ba[2 * e] : bb[2 * e - 4], bh = e < 2 ? ba[2 * e + 1] : bb[2 * e - 3];
;             const float vl = bl + wl0 * lo16(xm[e]) + wl1 * lo16(x0[e]) + wl2 * lo16(xp[e]);
;             const float vh = bh + wh0 * hi16(xm[e]) + wh1 * hi16(x0[e]) + wh2 * hi16(xp[e]);
;             o[e] = cvtpk(silu_fast(vl), silu_fast(vh));
;         }
;         put(r0 + rr, o);
;     }
	v_add_f32_e32 v123, 1.0, v123
	v_rcp_f32_e32 v157, v123
	s_nop 0
	v_pk_mul_f32 v[150:151], v[150:151], v[156:157]
	s_nop 0
	v_cvt_pk_bf16_f32 v123, v150, v151
	ds_write_b128 v149, v[120:123]
	v_pk_fma_f32 v[120:121], v[32:33], v[134:135], v[48:49]
	v_lshlrev_b32_e32 v122, 16, v60
	v_pk_fma_f32 v[120:121], v[36:37], v[132:133], v[120:121]
	v_and_b32_e32 v123, 0xffff0000, v60
	v_pk_fma_f32 v[120:121], v[40:41], v[122:123], v[120:121]
	s_nop 0
	v_mul_f32_e32 v60, 0xbfb8aa3b, v120
	v_exp_f32_e32 v60, v60
	s_nop 0
	v_add_f32_e32 v60, 1.0, v60
	v_rcp_f32_e32 v134, v60
	v_mul_f32_e32 v60, 0xbfb8aa3b, v121
	v_exp_f32_e32 v60, v60
	s_nop 0
	v_add_f32_e32 v60, 1.0, v60
	v_rcp_f32_e32 v135, v60
	s_nop 0
	v_pk_mul_f32 v[120:121], v[120:121], v[134:135]
	s_nop 0
	v_cvt_pk_bf16_f32 v150, v120, v121
	v_pk_fma_f32 v[120:121], v[34:35], v[136:137], v[50:51]
	v_lshlrev_b32_e32 v136, 16, v62
	v_pk_fma_f32 v[134:135], v[38:39], v[124:125], v[120:121]
	v_lshlrev_b32_e32 v120, 16, v61
	v_and_b32_e32 v121, 0xffff0000, v61
	v_pk_fma_f32 v[60:61], v[42:43], v[120:121], v[134:135]
	v_and_b32_e32 v137, 0xffff0000, v62
	v_mul_f32_e32 v134, 0xbfb8aa3b, v60
	v_mul_f32_e32 v135, 0xbfb8aa3b, v61
	v_exp_f32_e32 v134, v134
	v_exp_f32_e32 v135, v135
	v_add_f32_e32 v134, 1.0, v134
	v_add_f32_e32 v135, 1.0, v135
	v_rcp_f32_e32 v134, v134
	v_rcp_f32_e32 v135, v135
	s_nop 0
	v_pk_mul_f32 v[60:61], v[60:61], v[134:135]
	s_nop 0
	v_cvt_pk_bf16_f32 v151, v60, v61
	v_pk_fma_f32 v[60:61], v[12:13], v[152:153], v[28:29]
	s_nop 0
	v_pk_fma_f32 v[60:61], v[24:25], v[138:139], v[60:61]
	s_nop 0
	v_pk_fma_f32 v[60:61], v[20:21], v[136:137], v[60:61]
	s_nop 0
	v_mul_f32_e32 v62, 0xbfb8aa3b, v60
	v_exp_f32_e32 v62, v62
	s_nop 0
	v_add_f32_e32 v62, 1.0, v62
	v_rcp_f32_e32 v134, v62
	v_mul_f32_e32 v62, 0xbfb8aa3b, v61
	v_exp_f32_e32 v62, v62
	s_nop 0
	v_add_f32_e32 v62, 1.0, v62
	v_rcp_f32_e32 v135, v62
	s_nop 0
	v_pk_mul_f32 v[60:61], v[60:61], v[134:135]
	s_nop 0
	v_cvt_pk_bf16_f32 v152, v60, v61
	v_pk_fma_f32 v[60:61], v[14:15], v[154:155], v[30:31]
	s_nop 0
	v_pk_fma_f32 v[134:135], v[26:27], v[126:127], v[60:61]
	v_lshlrev_b32_e32 v60, 16, v63
	v_and_b32_e32 v61, 0xffff0000, v63
	v_pk_fma_f32 v[62:63], v[22:23], v[60:61], v[134:135]
	s_nop 0
	v_mul_f32_e32 v134, 0xbfb8aa3b, v62
	v_mul_f32_e32 v135, 0xbfb8aa3b, v63
	v_exp_f32_e32 v134, v134
	v_exp_f32_e32 v135, v135
	v_add_f32_e32 v134, 1.0, v134
	v_add_f32_e32 v135, 1.0, v135
	v_rcp_f32_e32 v134, v134
	v_rcp_f32_e32 v135, v135
	s_nop 0
	v_pk_mul_f32 v[62:63], v[62:63], v[134:135]
	s_nop 0
	v_cvt_pk_bf16_f32 v153, v62, v63
	v_pk_fma_f32 v[62:63], v[32:33], v[132:133], v[48:49]
	v_lshlrev_b32_e32 v134, 16, v56
	v_pk_fma_f32 v[62:63], v[36:37], v[122:123], v[62:63]
	v_and_b32_e32 v135, 0xffff0000, v56
	v_pk_fma_f32 v[62:63], v[40:41], v[134:135], v[62:63]
	ds_write_b128 v149, v[150:153] offset:64
	v_mul_f32_e32 v56, 0xbfb8aa3b, v62
	v_exp_f32_e32 v56, v56
	s_nop 0
	v_add_f32_e32 v56, 1.0, v56
	v_rcp_f32_e32 v132, v56
	v_mul_f32_e32 v56, 0xbfb8aa3b, v63
	v_exp_f32_e32 v56, v56
	s_nop 0
	v_add_f32_e32 v56, 1.0, v56
	v_rcp_f32_e32 v133, v56
	v_lshlrev_b32_e32 v56, 16, v57
	v_and_b32_e32 v57, 0xffff0000, v57
	v_pk_mul_f32 v[62:63], v[62:63], v[132:133]
	s_nop 0
	v_cvt_pk_bf16_f32 v150, v62, v63
	v_pk_fma_f32 v[62:63], v[34:35], v[124:125], v[50:51]
	v_lshlrev_b32_e32 v132, 16, v58
	v_pk_fma_f32 v[62:63], v[38:39], v[120:121], v[62:63]
	v_and_b32_e32 v133, 0xffff0000, v58
	v_pk_fma_f32 v[62:63], v[42:43], v[56:57], v[62:63]
	s_nop 0
	v_mul_f32_e32 v124, 0xbfb8aa3b, v62
	v_mul_f32_e32 v125, 0xbfb8aa3b, v63
	v_exp_f32_e32 v124, v124
	v_exp_f32_e32 v125, v125
	v_add_f32_e32 v124, 1.0, v124
	v_add_f32_e32 v125, 1.0, v125
	v_rcp_f32_e32 v124, v124
	v_rcp_f32_e32 v125, v125
	s_nop 0
	v_pk_mul_f32 v[62:63], v[62:63], v[124:125]
	s_nop 0
	v_cvt_pk_bf16_f32 v151, v62, v63
	v_pk_fma_f32 v[62:63], v[12:13], v[138:139], v[28:29]
	s_nop 0
	v_pk_fma_f32 v[62:63], v[24:25], v[136:137], v[62:63]
	s_nop 0
	v_pk_fma_f32 v[62:63], v[20:21], v[132:133], v[62:63]
	s_nop 0
	v_mul_f32_e32 v58, 0xbfb8aa3b, v62
	v_exp_f32_e32 v58, v58
	s_nop 0
	v_add_f32_e32 v58, 1.0, v58
	v_rcp_f32_e32 v124, v58
	v_mul_f32_e32 v58, 0xbfb8aa3b, v63
	v_exp_f32_e32 v58, v58
	s_nop 0
	v_add_f32_e32 v58, 1.0, v58
	v_rcp_f32_e32 v125, v58
	s_nop 0
	v_pk_mul_f32 v[62:63], v[62:63], v[124:125]
	s_nop 0
	v_cvt_pk_bf16_f32 v152, v62, v63
	v_pk_fma_f32 v[62:63], v[14:15], v[126:127], v[30:31]
	v_lshlrev_b32_e32 v124, 16, v59
	v_pk_fma_f32 v[62:63], v[26:27], v[60:61], v[62:63]
	v_and_b32_e32 v125, 0xffff0000, v59
	v_pk_fma_f32 v[58:59], v[22:23], v[124:125], v[62:63]
	s_nop 0
	v_mul_f32_e32 v62, 0xbfb8aa3b, v58
	v_mul_f32_e32 v63, 0xbfb8aa3b, v59
	v_exp_f32_e32 v62, v62
	v_exp_f32_e32 v63, v63
	v_add_f32_e32 v62, 1.0, v62
	v_add_f32_e32 v63, 1.0, v63
	v_rcp_f32_e32 v62, v62
	v_rcp_f32_e32 v63, v63
	s_nop 0
	v_pk_mul_f32 v[58:59], v[58:59], v[62:63]
	s_nop 0
	v_cvt_pk_bf16_f32 v153, v58, v59
	v_pk_fma_f32 v[58:59], v[32:33], v[122:123], v[48:49]
	v_lshlrev_b32_e32 v122, 16, v52
	v_pk_fma_f32 v[58:59], v[36:37], v[134:135], v[58:59]
	v_and_b32_e32 v123, 0xffff0000, v52
	v_pk_fma_f32 v[58:59], v[40:41], v[122:123], v[58:59]
	ds_write_b128 v149, v[150:153] offset:128
	v_mul_f32_e32 v52, 0xbfb8aa3b, v58
	v_exp_f32_e32 v52, v52
	s_nop 0
	v_add_f32_e32 v52, 1.0, v52
	v_rcp_f32_e32 v62, v52
	v_mul_f32_e32 v52, 0xbfb8aa3b, v59
	v_exp_f32_e32 v52, v52
	s_nop 0
	v_add_f32_e32 v52, 1.0, v52
	v_rcp_f32_e32 v63, v52
	s_nop 0
	v_pk_mul_f32 v[58:59], v[58:59], v[62:63]
	s_nop 0
	v_cvt_pk_bf16_f32 v52, v58, v59
	v_pk_fma_f32 v[58:59], v[34:35], v[120:121], v[50:51]
	v_lshlrev_b32_e32 v120, 16, v53
; __device__ __forceinline__ unsigned cvtpk(float lo, float hi) { f32x2_t v = {lo, hi}; bf16x2_t b = __builtin_convertvector(v, bf16x2_t); return __builtin_bit_cast(unsigned, b); }
; __device__ __forceinline__ float lo16(unsigned u) { return __uint_as_float(u << 16); }
; __device__ __forceinline__ float hi16(unsigned u) { return __uint_as_float(u & 0xffff0000u); }
; __device__ __forceinline__ float silu_fast(float v) { return v * __builtin_amdgcn_rcpf(1.f + __builtin_amdgcn_exp2f(-v * LOG2E)); }
; __device__ __forceinline__ unsigned cvtpk(float lo, float hi) { f32x2_t v = {lo, hi}; bf16x2_t b = __builtin_convertvector(v, bf16x2_t); return __builtin_bit_cast(unsigned, b); }
; __device__ __forceinline__ float lo16(unsigned u) { return __uint_as_float(u << 16); }
; __device__ __forceinline__ float hi16(unsigned u) { return __uint_as_float(u & 0xffff0000u); }
; __device__ __forceinline__ float silu_fast(float v) { return v * __builtin_amdgcn_rcpf(1.f + __builtin_amdgcn_exp2f(-v * LOG2E)); }
; template <class Put>
; __device__ __forceinline__ void conv_compute(const ConvRaw& R, const float* cw, const float* cb, int col0, int rg, const Put& put) {
;     ...
;     for (int rr = 0; rr < 8; ++rr) {
;         const u32x4 xm = R.r[rr], x0 = R.r[rr + 1], xp = R.r[rr + 2]; u32x4 o;
; #pragma unroll
;         for (int e = 0; e < 4; ++e) {
;             const float wl0 = e < 2 ? w0a[2 * e] : w0b[2 * e - 4], wh0 = e < 2 ? w0a[2 * e + 1] : w0b[2 * e - 3];
;             const float wl1 = e < 2 ? w1a[2 * e] : w1b[2 * e - 4], wh1 = e < 2 ? w1a[2 * e + 1] : w1b[2 * e - 3];
;             const float wl2 = e < 2 ? w2a[2 * e] : w2b[2 * e - 4], wh2 = e < 2 ? w2a[2 * e + 1] : w2b[2 * e - 3];
;             const float bl = e < 2 ? ba[2 * e] : bb[2 * e - 4], bh = e < 2 ? ba[2 * e + 1] : bb[2 * e - 3];
;             const float vl = bl + wl0 * lo16(xm[e]) + wl1 * lo16(x0[e]) + wl2 * lo16(xp[e]);
;             const float vh = bh + wh0 * hi16(xm[e]) + wh1 * hi16(x0[e]) + wh2 * hi16(xp[e]);
;             o[e] = cvtpk(silu_fast(vl), silu_fast(vh));
;         }
;         put(r0 + rr, o);
;     }
	v_pk_fma_f32 v[58:59], v[38:39], v[56:57], v[58:59]
	v_and_b32_e32 v121, 0xffff0000, v53
	v_pk_fma_f32 v[58:59], v[42:43], v[120:121], v[58:59]
	s_nop 0
	v_mul_f32_e32 v53, 0xbfb8aa3b, v58
	v_exp_f32_e32 v53, v53
	s_nop 0
	v_add_f32_e32 v53, 1.0, v53
	v_rcp_f32_e32 v62, v53
	v_mul_f32_e32 v53, 0xbfb8aa3b, v59
	v_exp_f32_e32 v53, v53
	s_nop 0
	v_add_f32_e32 v53, 1.0, v53
	v_rcp_f32_e32 v63, v53
	s_nop 0
	v_pk_mul_f32 v[58:59], v[58:59], v[62:63]
	s_nop 0
	v_cvt_pk_bf16_f32 v53, v58, v59
	v_pk_fma_f32 v[58:59], v[12:13], v[136:137], v[28:29]
	v_lshlrev_b32_e32 v62, 16, v54
	v_pk_fma_f32 v[58:59], v[24:25], v[132:133], v[58:59]
	v_and_b32_e32 v63, 0xffff0000, v54
	v_pk_fma_f32 v[58:59], v[20:21], v[62:63], v[58:59]
	s_nop 0
	v_mul_f32_e32 v54, 0xbfb8aa3b, v58
	v_exp_f32_e32 v54, v54
	s_nop 0
	v_add_f32_e32 v54, 1.0, v54
	v_rcp_f32_e32 v126, v54
	v_mul_f32_e32 v54, 0xbfb8aa3b, v59
	v_exp_f32_e32 v54, v54
	s_nop 0
	v_add_f32_e32 v54, 1.0, v54
	v_rcp_f32_e32 v127, v54
	s_nop 0
	v_pk_mul_f32 v[58:59], v[58:59], v[126:127]
	s_nop 0
	v_cvt_pk_bf16_f32 v54, v58, v59
	v_pk_fma_f32 v[58:59], v[14:15], v[60:61], v[30:31]
	v_lshlrev_b32_e32 v60, 16, v55
	v_pk_fma_f32 v[58:59], v[26:27], v[124:125], v[58:59]
	v_and_b32_e32 v61, 0xffff0000, v55
	v_pk_fma_f32 v[58:59], v[22:23], v[60:61], v[58:59]
	s_nop 0
	v_mul_f32_e32 v55, 0xbfb8aa3b, v58
	v_exp_f32_e32 v55, v55
	s_nop 0
	v_add_f32_e32 v55, 1.0, v55
	v_rcp_f32_e32 v126, v55
	v_mul_f32_e32 v55, 0xbfb8aa3b, v59
	v_exp_f32_e32 v55, v55
	s_nop 0
	v_add_f32_e32 v55, 1.0, v55
	v_rcp_f32_e32 v127, v55
	s_nop 0
	v_pk_mul_f32 v[58:59], v[58:59], v[126:127]
	s_nop 0
	v_cvt_pk_bf16_f32 v55, v58, v59
	ds_write_b128 v149, v[52:55] offset:192
	v_pk_fma_f32 v[52:53], v[32:33], v[134:135], v[48:49]
	v_lshlrev_b32_e32 v58, 16, v44
	v_pk_fma_f32 v[52:53], v[36:37], v[122:123], v[52:53]
	v_and_b32_e32 v59, 0xffff0000, v44
	v_pk_fma_f32 v[52:53], v[40:41], v[58:59], v[52:53]
	s_nop 0
	v_mul_f32_e32 v44, 0xbfb8aa3b, v52
	v_exp_f32_e32 v44, v44
	s_nop 0
	v_add_f32_e32 v44, 1.0, v44
	v_rcp_f32_e32 v54, v44
	v_mul_f32_e32 v44, 0xbfb8aa3b, v53
	v_exp_f32_e32 v44, v44
	s_nop 0
	v_add_f32_e32 v44, 1.0, v44
	v_rcp_f32_e32 v55, v44
	s_nop 0
	v_pk_mul_f32 v[52:53], v[52:53], v[54:55]
	s_nop 0
	v_cvt_pk_bf16_f32 v44, v52, v53
	v_pk_fma_f32 v[52:53], v[34:35], v[56:57], v[50:51]
	v_lshlrev_b32_e32 v56, 16, v45
	v_pk_fma_f32 v[52:53], v[38:39], v[120:121], v[52:53]
	v_and_b32_e32 v57, 0xffff0000, v45
	v_pk_fma_f32 v[52:53], v[42:43], v[56:57], v[52:53]
	s_nop 0
	v_mul_f32_e32 v45, 0xbfb8aa3b, v52
	v_exp_f32_e32 v45, v45
	s_nop 0
	v_add_f32_e32 v45, 1.0, v45
	v_rcp_f32_e32 v54, v45
	v_mul_f32_e32 v45, 0xbfb8aa3b, v53
	v_exp_f32_e32 v45, v45
	s_nop 0
	v_add_f32_e32 v45, 1.0, v45
	v_rcp_f32_e32 v55, v45
	s_nop 0
	v_pk_mul_f32 v[52:53], v[52:53], v[54:55]
	s_nop 0
	v_cvt_pk_bf16_f32 v45, v52, v53
	v_pk_fma_f32 v[52:53], v[12:13], v[132:133], v[28:29]
	v_lshlrev_b32_e32 v54, 16, v46
	v_pk_fma_f32 v[52:53], v[24:25], v[62:63], v[52:53]
	v_and_b32_e32 v55, 0xffff0000, v46
	v_pk_fma_f32 v[52:53], v[20:21], v[54:55], v[52:53]
	v_and_b32_e32 v132, 15, v224
	v_mul_f32_e32 v46, 0xbfb8aa3b, v52
	v_exp_f32_e32 v46, v46
	s_nop 0
	v_add_f32_e32 v46, 1.0, v46
	v_rcp_f32_e32 v126, v46
	v_mul_f32_e32 v46, 0xbfb8aa3b, v53
	v_exp_f32_e32 v46, v46
	s_nop 0
	v_add_f32_e32 v46, 1.0, v46
	v_rcp_f32_e32 v127, v46
	s_nop 0
	v_pk_mul_f32 v[52:53], v[52:53], v[126:127]
	s_nop 0
	v_cvt_pk_bf16_f32 v46, v52, v53
	v_pk_fma_f32 v[52:53], v[14:15], v[124:125], v[30:31]
	s_nop 0
	v_pk_fma_f32 v[124:125], v[26:27], v[60:61], v[52:53]
	v_lshlrev_b32_e32 v52, 16, v47
	v_and_b32_e32 v53, 0xffff0000, v47
	v_pk_fma_f32 v[124:125], v[22:23], v[52:53], v[124:125]
	v_pk_fma_f32 v[60:61], v[14:15], v[60:61], v[30:31]
	v_mul_f32_e32 v47, 0xbfb8aa3b, v124
	v_exp_f32_e32 v47, v47
	v_pk_fma_f32 v[60:61], v[26:27], v[52:53], v[60:61]
	v_pk_fma_f32 v[52:53], v[14:15], v[52:53], v[30:31]
	v_add_f32_e32 v47, 1.0, v47
	v_rcp_f32_e32 v126, v47
	v_mul_f32_e32 v47, 0xbfb8aa3b, v125
	v_exp_f32_e32 v47, v47
	s_nop 0
	v_add_f32_e32 v47, 1.0, v47
	v_rcp_f32_e32 v127, v47
	s_nop 0
	v_pk_mul_f32 v[124:125], v[124:125], v[126:127]
	s_nop 0
	v_cvt_pk_bf16_f32 v47, v124, v125
	ds_write_b128 v149, v[44:47] offset:256
	v_pk_fma_f32 v[44:45], v[32:33], v[122:123], v[48:49]
	v_lshlrev_b32_e32 v46, 16, v8
	v_pk_fma_f32 v[44:45], v[36:37], v[58:59], v[44:45]
	v_and_b32_e32 v47, 0xffff0000, v8
	v_pk_fma_f32 v[44:45], v[40:41], v[46:47], v[44:45]
	v_pk_fma_f32 v[58:59], v[32:33], v[58:59], v[48:49]
	v_mul_f32_e32 v8, 0xbfb8aa3b, v44
	v_exp_f32_e32 v8, v8
	v_pk_fma_f32 v[58:59], v[36:37], v[46:47], v[58:59]
	v_add_f32_e32 v8, 1.0, v8
	v_rcp_f32_e32 v122, v8
	v_mul_f32_e32 v8, 0xbfb8aa3b, v45
	v_exp_f32_e32 v8, v8
	s_nop 0
	v_add_f32_e32 v8, 1.0, v8
	v_rcp_f32_e32 v123, v8
	s_nop 0
	v_pk_mul_f32 v[44:45], v[44:45], v[122:123]
	s_nop 0
	v_cvt_pk_bf16_f32 v122, v44, v45
	v_pk_fma_f32 v[44:45], v[34:35], v[120:121], v[50:51]
	s_nop 0
	v_pk_fma_f32 v[120:121], v[38:39], v[56:57], v[44:45]
	v_lshlrev_b32_e32 v44, 16, v9
	v_and_b32_e32 v45, 0xffff0000, v9
	v_pk_fma_f32 v[8:9], v[42:43], v[44:45], v[120:121]
	v_pk_fma_f32 v[56:57], v[34:35], v[56:57], v[50:51]
	v_mul_f32_e32 v120, 0xbfb8aa3b, v8
	v_mul_f32_e32 v121, 0xbfb8aa3b, v9
	v_exp_f32_e32 v120, v120
	v_exp_f32_e32 v121, v121
	v_pk_fma_f32 v[56:57], v[38:39], v[44:45], v[56:57]
	v_add_f32_e32 v120, 1.0, v120
	v_add_f32_e32 v121, 1.0, v121
	v_rcp_f32_e32 v120, v120
	v_rcp_f32_e32 v121, v121
	s_nop 0
	v_pk_mul_f32 v[8:9], v[8:9], v[120:121]
	s_nop 0
	v_cvt_pk_bf16_f32 v123, v8, v9
	v_pk_fma_f32 v[8:9], v[12:13], v[62:63], v[28:29]
	s_nop 0
; #define LAS __attribute__((address_space(3)))
; __device__ __forceinline__ unsigned cvtpk(float lo, float hi) { f32x2_t v = {lo, hi}; bf16x2_t b = __builtin_convertvector(v, bf16x2_t); return __builtin_bit_cast(unsigned, b); }
; template <class Put>
; __device__ __forceinline__ void conv_compute(const ConvRaw& R, const float* cw, const float* cb, int col0, int rg, const Put& put) {
;     ...
;     for (int rr = 0; rr < 8; ++rr) {
;         const u32x4 xm = R.r[rr], x0 = R.r[rr + 1], xp = R.r[rr + 2]; u32x4 o;
; #pragma unroll
;         for (int e = 0; e < 4; ++e) {
;             const float wl0 = e < 2 ? w0a[2 * e] : w0b[2 * e - 4], wh0 = e < 2 ? w0a[2 * e + 1] : w0b[2 * e - 3];
;             const float wl1 = e < 2 ? w1a[2 * e] : w1b[2 * e - 4], wh1 = e < 2 ? w1a[2 * e + 1] : w1b[2 * e - 3];
;             const float wl2 = e < 2 ? w2a[2 * e] : w2b[2 * e - 4], wh2 = e < 2 ? w2a[2 * e + 1] : w2b[2 * e - 3];
;             const float bl = e < 2 ? ba[2 * e] : bb[2 * e - 4], bh = e < 2 ? ba[2 * e + 1] : bb[2 * e - 3];
;             const float vl = bl + wl0 * lo16(xm[e]) + wl1 * lo16(x0[e]) + wl2 * lo16(xp[e]);
;             const float vh = bh + wh0 * hi16(xm[e]) + wh1 * hi16(x0[e]) + wh2 * hi16(xp[e]);
;             o[e] = cvtpk(silu_fast(vl), silu_fast(vh));
;         }
;         put(r0 + rr, o);
;     }
; template <class Wait>
; __device__ __forceinline__ void out_unit(Frame& F, const Ptrs& P, int b, int c, int g, const Wait& wait) {
;     ...
;     __syncthreads();
;     }
;     const LAS float* Vf = (const LAS float*)(lds + L_VEC) + (hl * 2 + 0) * 512; const LAS float* Vb = (const LAS float*)(lds + L_VEC) + (hl * 2 + 1) * 512;
;     const LAS unsigned char* xsb = lds + L_XS + hl * 16384 + ((lane >> 4) & 1) * 32 + (lane & 3) * 8 + (4 * hi + ((lane & 15) >> 2)) * 64;
;     const int q0 = 64 * qh + r32, q1 = q0 + 32;
;     const LAS unsigned char* crow0 = lds + L_CIMG + q0 * 256; const LAS unsigned char* crow1 = lds + L_CIMG + q1 * 256;
;     f32x16 y[2][2];
; #pragma unroll
;     for (int i = 0; i < 2; ++i)
; #pragma unroll
;         for (int j = 0; j < 2; ++j) y[i][j] = f32x16{};
; #pragma unroll
;     for (int ks = 0; ks < 8; ++ks) { const int chn = 2 * ks + hi;
;         const bf16x8 c0 = *(const LAS bf16x8*)(crow0 + ((chn ^ (q0 & 15)) * 16)), c1 = *(const LAS bf16x8*)(crow1 + ((chn ^ (q1 & 15)) * 16));
	v_pk_fma_f32 v[62:63], v[24:25], v[54:55], v[8:9]
	v_lshlrev_b32_e32 v8, 16, v10
	v_and_b32_e32 v9, 0xffff0000, v10
	v_pk_fma_f32 v[62:63], v[20:21], v[8:9], v[62:63]
	v_pk_fma_f32 v[54:55], v[12:13], v[54:55], v[28:29]
	v_mul_f32_e32 v10, 0xbfb8aa3b, v62
	v_exp_f32_e32 v10, v10
	v_pk_fma_f32 v[54:55], v[24:25], v[8:9], v[54:55]
	v_pk_fma_f32 v[8:9], v[12:13], v[8:9], v[28:29]
	v_add_f32_e32 v10, 1.0, v10
	v_rcp_f32_e32 v120, v10
	v_mul_f32_e32 v10, 0xbfb8aa3b, v63
	v_exp_f32_e32 v10, v10
	s_nop 0
	v_add_f32_e32 v10, 1.0, v10
	v_rcp_f32_e32 v121, v10
	v_lshlrev_b32_e32 v10, 16, v11
	v_and_b32_e32 v11, 0xffff0000, v11
	v_pk_fma_f32 v[60:61], v[22:23], v[10:11], v[60:61]
	v_pk_mul_f32 v[62:63], v[62:63], v[120:121]
	v_pk_fma_f32 v[52:53], v[26:27], v[10:11], v[52:53]
	v_cvt_pk_bf16_f32 v124, v62, v63
	v_mul_f32_e32 v62, 0xbfb8aa3b, v60
	v_mul_f32_e32 v63, 0xbfb8aa3b, v61
	v_exp_f32_e32 v62, v62
	v_exp_f32_e32 v63, v63
	v_or_b32_e32 v120, 32, v202
	v_lshlrev_b32_e32 v121, 8, v202
	v_add_f32_e32 v62, 1.0, v62
	v_add_f32_e32 v63, 1.0, v63
	v_rcp_f32_e32 v62, v62
	v_rcp_f32_e32 v63, v63
	s_nop 0
	v_pk_mul_f32 v[60:61], v[60:61], v[62:63]
	s_nop 0
	v_cvt_pk_bf16_f32 v125, v60, v61
	v_lshlrev_b32_e32 v60, 16, v4
	v_and_b32_e32 v61, 0xffff0000, v4
	v_pk_fma_f32 v[58:59], v[40:41], v[60:61], v[58:59]
	ds_write_b128 v149, v[122:125] offset:320
	v_mul_f32_e32 v4, 0xbfb8aa3b, v58
	v_exp_f32_e32 v4, v4
	v_lshlrev_b32_e32 v122, 8, v120
	v_add_f32_e32 v4, 1.0, v4
	v_rcp_f32_e32 v62, v4
	v_mul_f32_e32 v4, 0xbfb8aa3b, v59
	v_exp_f32_e32 v4, v4
	s_nop 0
	v_add_f32_e32 v4, 1.0, v4
	v_rcp_f32_e32 v63, v4
	s_nop 0
	v_pk_mul_f32 v[58:59], v[58:59], v[62:63]
	s_nop 0
	v_cvt_pk_bf16_f32 v4, v58, v59
	v_lshlrev_b32_e32 v58, 16, v5
	v_and_b32_e32 v59, 0xffff0000, v5
	v_pk_fma_f32 v[56:57], v[42:43], v[58:59], v[56:57]
	s_nop 0
	v_mul_f32_e32 v5, 0xbfb8aa3b, v56
	v_exp_f32_e32 v5, v5
	s_nop 0
	v_add_f32_e32 v5, 1.0, v5
	v_rcp_f32_e32 v62, v5
	v_mul_f32_e32 v5, 0xbfb8aa3b, v57
	v_exp_f32_e32 v5, v5
	s_nop 0
	v_add_f32_e32 v5, 1.0, v5
	v_rcp_f32_e32 v63, v5
	s_nop 0
	v_pk_mul_f32 v[56:57], v[56:57], v[62:63]
	s_nop 0
	v_cvt_pk_bf16_f32 v5, v56, v57
	v_lshlrev_b32_e32 v56, 16, v6
	v_and_b32_e32 v57, 0xffff0000, v6
	v_pk_fma_f32 v[54:55], v[20:21], v[56:57], v[54:55]
	v_pk_fma_f32 v[8:9], v[24:25], v[56:57], v[8:9]
	v_mul_f32_e32 v6, 0xbfb8aa3b, v54
	v_exp_f32_e32 v6, v6
	s_nop 0
	v_add_f32_e32 v6, 1.0, v6
	v_rcp_f32_e32 v62, v6
	v_mul_f32_e32 v6, 0xbfb8aa3b, v55
	v_exp_f32_e32 v6, v6
	s_nop 0
	v_add_f32_e32 v6, 1.0, v6
	v_rcp_f32_e32 v63, v6
	s_nop 0
	v_pk_mul_f32 v[54:55], v[54:55], v[62:63]
	s_nop 0
	v_cvt_pk_bf16_f32 v6, v54, v55
	v_lshlrev_b32_e32 v54, 16, v7
	v_and_b32_e32 v55, 0xffff0000, v7
	v_pk_fma_f32 v[52:53], v[22:23], v[54:55], v[52:53]
	s_nop 0
	v_mul_f32_e32 v7, 0xbfb8aa3b, v52
	v_exp_f32_e32 v7, v7
	s_nop 0
	v_add_f32_e32 v7, 1.0, v7
	v_rcp_f32_e32 v62, v7
	v_mul_f32_e32 v7, 0xbfb8aa3b, v53
	v_exp_f32_e32 v7, v7
	s_nop 0
	v_add_f32_e32 v7, 1.0, v7
	v_rcp_f32_e32 v63, v7
	s_nop 0
	v_pk_mul_f32 v[52:53], v[52:53], v[62:63]
	s_nop 0
	v_cvt_pk_bf16_f32 v7, v52, v53
	ds_write_b128 v149, v[4:7] offset:384
	v_pk_fma_f32 v[6:7], v[32:33], v[46:47], v[48:49]
	v_lshlrev_b32_e32 v4, 16, v148
	v_and_b32_e32 v5, 0xffff0000, v148
	v_pk_fma_f32 v[6:7], v[36:37], v[60:61], v[6:7]
	v_pk_fma_f32 v[32:33], v[34:35], v[44:45], v[50:51]
	v_pk_fma_f32 v[4:5], v[40:41], v[4:5], v[6:7]
	v_pk_fma_f32 v[32:33], v[38:39], v[58:59], v[32:33]
	v_mul_f32_e32 v6, 0xbfb8aa3b, v4
	v_mul_f32_e32 v7, 0xbfb8aa3b, v5
	v_exp_f32_e32 v6, v6
	v_exp_f32_e32 v7, v7
	v_add_f32_e32 v6, 1.0, v6
	v_add_f32_e32 v7, 1.0, v7
	v_rcp_f32_e32 v6, v6
	v_rcp_f32_e32 v7, v7
	s_nop 0
	v_pk_mul_f32 v[4:5], v[4:5], v[6:7]
	v_lshlrev_b32_e32 v6, 16, v147
	v_and_b32_e32 v7, 0xffff0000, v147
	v_pk_fma_f32 v[6:7], v[42:43], v[6:7], v[32:33]
	v_cvt_pk_bf16_f32 v4, v4, v5
	v_mul_f32_e32 v5, 0xbfb8aa3b, v6
	v_exp_f32_e32 v5, v5
	s_nop 0
	v_add_f32_e32 v5, 1.0, v5
	v_rcp_f32_e32 v32, v5
	v_mul_f32_e32 v5, 0xbfb8aa3b, v7
	v_exp_f32_e32 v5, v5
	s_nop 0
	v_add_f32_e32 v5, 1.0, v5
	v_rcp_f32_e32 v33, v5
	s_nop 0
	v_pk_mul_f32 v[6:7], v[6:7], v[32:33]
	s_nop 0
	v_cvt_pk_bf16_f32 v5, v6, v7
	v_lshlrev_b32_e32 v6, 16, v146
	v_and_b32_e32 v7, 0xffff0000, v146
	v_pk_fma_f32 v[6:7], v[20:21], v[6:7], v[8:9]
	s_nop 0
	v_mul_f32_e32 v8, 0xbfb8aa3b, v6
	v_mul_f32_e32 v9, 0xbfb8aa3b, v7
	v_exp_f32_e32 v8, v8
	v_exp_f32_e32 v9, v9
	v_add_f32_e32 v8, 1.0, v8
	v_add_f32_e32 v9, 1.0, v9
	v_rcp_f32_e32 v8, v8
	v_rcp_f32_e32 v9, v9
	s_nop 0
	v_pk_mul_f32 v[6:7], v[6:7], v[8:9]
	v_pk_fma_f32 v[8:9], v[14:15], v[10:11], v[30:31]
	v_lshlrev_b32_e32 v10, 16, v145
	v_pk_fma_f32 v[8:9], v[26:27], v[54:55], v[8:9]
	v_and_b32_e32 v11, 0xffff0000, v145
	v_pk_fma_f32 v[8:9], v[22:23], v[10:11], v[8:9]
	v_cvt_pk_bf16_f32 v6, v6, v7
	v_mul_f32_e32 v7, 0xbfb8aa3b, v8
	v_exp_f32_e32 v7, v7
	s_nop 0
	v_add_f32_e32 v7, 1.0, v7
	v_rcp_f32_e32 v10, v7
	v_mul_f32_e32 v7, 0xbfb8aa3b, v9
	v_exp_f32_e32 v7, v7
	s_nop 0
	v_add_f32_e32 v7, 1.0, v7
	v_rcp_f32_e32 v11, v7
	s_nop 0
	v_pk_mul_f32 v[8:9], v[8:9], v[10:11]
	s_nop 0
	v_cvt_pk_bf16_f32 v7, v8, v9
	ds_write_b128 v149, v[4:7] offset:448
	v_bitop3_b32 v4, v223, v224, 15 bitop3:0x78
	v_lshlrev_b32_e32 v123, 4, v4
	v_bitop3_b32 v4, v223, v132, 2 bitop3:0x36
	v_lshlrev_b32_e32 v124, 4, v4
	v_bitop3_b32 v4, v223, v132, 4 bitop3:0x36
	v_lshlrev_b32_e32 v125, 4, v4
	v_bitop3_b32 v4, v223, v132, 6 bitop3:0x36
	v_lshlrev_b32_e32 v126, 4, v4
	v_bitop3_b32 v4, v223, v132, 8 bitop3:0x36
	v_lshlrev_b32_e32 v127, 4, v4
	v_bitop3_b32 v4, v223, v132, 10 bitop3:0x36
	v_lshlrev_b32_e32 v133, 4, v4
	v_bitop3_b32 v4, v223, v132, 12 bitop3:0x36
	v_lshlrev_b32_e32 v134, 4, v4
	v_bitop3_b32 v4, v223, v132, 14 bitop3:0x36
	v_lshlrev_b32_e32 v135, 4, v4
	s_waitcnt lgkmcnt(0)
	s_barrier
